# v49: ssd_out D-skip load issued before the S3 prefetch loads; its late wait is counted per case so S3 loads stay in flight until the loop-end wait
# speedup vs baseline: 1.0057x; 1.0057x over previous
.LBB0_1337:
	global_load_dword v238, v99, s[54:55]
	s_cmp_lg_u32 s33, 12
	s_cselect_b64 s[66:67], -1, 0
	s_cmp_eq_u32 s33, 12
	s_cbranch_scc1 .LBB0_1345
	v_readlane_b32 s36, v254, 63
	v_readlane_b32 s50, v255, 13
	v_readlane_b32 s51, v255, 14
	v_readlane_b32 s37, v255, 0
	v_readlane_b32 s38, v255, 1
	v_lshl_add_u64 v[66:67], s[50:51], 0, v[138:139]
	v_add_co_u32_e32 v38, vcc, 0xe800000, v66
	v_lshl_add_u64 v[64:65], s[50:51], 0, v[136:137]
	s_nop 0
	v_addc_co_u32_e32 v39, vcc, 0, v67, vcc
	v_add_co_u32_e32 v42, vcc, 0x25500000, v64
	v_lshl_add_u64 v[62:63], s[50:51], 0, v[132:133]
	s_nop 0
	v_addc_co_u32_e32 v43, vcc, 0, v65, vcc
	global_load_dwordx4 v[38:41], v[38:39], off offset:128
	s_nop 0
	global_load_dword v122, v[42:43], off offset:4
	v_add_co_u32_e32 v42, vcc, 0x20004000, v62
	v_readlane_b32 s39, v255, 2
	s_nop 0
	v_addc_co_u32_e32 v43, vcc, 0, v63, vcc
	global_load_dwordx4 v[42:45], v[42:43], off
	v_readlane_b32 s40, v255, 3
	v_readlane_b32 s41, v255, 4
	v_readlane_b32 s42, v255, 5
	v_readlane_b32 s43, v255, 6
	v_readlane_b32 s44, v255, 7
	v_readlane_b32 s45, v255, 8
	v_readlane_b32 s46, v255, 9
	v_readlane_b32 s47, v255, 10
	v_readlane_b32 s48, v255, 11
	v_readlane_b32 s49, v255, 12
	s_and_saveexec_b64 s[70:71], s[10:11]
	s_cbranch_execz .LBB0_1340
	v_add_co_u32_e32 v34, vcc, 0xe818000, v66
	s_nop 1
	v_addc_co_u32_e32 v35, vcc, 0, v67, vcc
	v_add_co_u32_e32 v54, vcc, 0x25500000, v64
	global_load_dwordx4 v[34:37], v[34:35], off offset:128
	s_nop 0
	v_addc_co_u32_e32 v55, vcc, 0, v65, vcc
	global_load_dword v124, v[54:55], off offset:2052

.LBB0_1346:
	v_readlane_b32 s36, v254, 63
	v_readlane_b32 s50, v255, 13
	v_readlane_b32 s51, v255, 14
	v_readlane_b32 s37, v255, 0
	v_readlane_b32 s38, v255, 1
	v_lshl_add_u64 v[66:67], s[70:71], 2, v[130:131]
	v_mov_b32_e32 v84, v240
	v_mov_b32_e32 v85, v241
	v_mov_b32_e32 v82, v242
	v_mov_b32_e32 v83, v243
	global_load_dword v240, v[66:67], off offset:4
	global_load_dword v241, v[66:67], off offset:68
	global_load_dword v242, v[66:67], off offset:132
	global_load_dword v243, v[66:67], off offset:196
	v_lshl_add_u64 v[70:71], s[50:51], 0, v[144:145]
	v_lshl_add_u64 v[70:71], v[70:71], 0, s[76:77]
	v_add_co_u32_e32 v66, vcc, 0x8c01000, v70
	v_readlane_b32 s39, v255, 2
	s_nop 0
	v_addc_co_u32_e32 v67, vcc, 0, v71, vcc
	v_add_co_u32_e32 v70, vcc, 0x8c18000, v70
	global_load_dwordx4 v[226:229], v[66:67], off offset:2048
	s_nop 0
	v_addc_co_u32_e32 v71, vcc, 0, v71, vcc
	global_load_dwordx4 v[230:233], v[70:71], off offset:2048
	s_and_b64 vcc, exec, s[6:7]
	v_readlane_b32 s40, v255, 3
	v_readlane_b32 s41, v255, 4
	v_readlane_b32 s42, v255, 5
	v_readlane_b32 s43, v255, 6
	v_readlane_b32 s44, v255, 7
	v_readlane_b32 s45, v255, 8
	v_readlane_b32 s46, v255, 9
	v_readlane_b32 s47, v255, 10
	v_readlane_b32 s48, v255, 11
	v_readlane_b32 s49, v255, 12
	v_add_u32_e32 v66, s33, v115
	v_add_u32_e32 v67, 0x1dc00, v66
	s_waitcnt lgkmcnt(0)
	s_barrier
	ds_read_b32 v152, v67
	v_add_u32_e32 v67, 0x1dc20, v66
	ds_read_b32 v153, v67
	v_add_u32_e32 v67, 0x1dc40, v66
	v_add_u32_e32 v66, 0x1dc60, v66
	ds_read_b32 v121, v67
	ds_read_b32 v119, v66
	v_add_u32_e32 v66, s33, v175
	v_add_u32_e32 v67, 0x1dc00, v66
	ds_read_b32 v67, v67
	s_waitcnt lgkmcnt(0)
	v_sub_f32_e32 v68, v152, v67
	v_mul_f32_e32 v68, 0x3fb8aa3b, v68
	v_exp_f32_e32 v68, v68
	s_nop 0
	v_mul_f32_e32 v68, v30, v68
	v_cvt_pk_bf16_f32 v68, v68, s0
	v_cndmask_b32_e64 v68, v68, 0, s[0:1]
	ds_write_b16 v181, v68
	v_sub_f32_e32 v68, v153, v67
	v_mul_f32_e32 v68, 0x3fb8aa3b, v68
	v_exp_f32_e32 v68, v68
	s_nop 0
	v_mul_f32_e32 v68, v31, v68
	v_cvt_pk_bf16_f32 v68, v68, s0
	v_cndmask_b32_e64 v68, v68, 0, s[18:19]
	ds_write_b16 v181, v68 offset:272
	v_sub_f32_e32 v68, v121, v67
	v_sub_f32_e32 v67, v119, v67
	v_mul_f32_e32 v67, 0x3fb8aa3b, v67
	v_exp_f32_e32 v67, v67
	v_mul_f32_e32 v68, 0x3fb8aa3b, v68
	v_exp_f32_e32 v68, v68
	v_mul_f32_e32 v67, v33, v67
	v_cvt_pk_bf16_f32 v67, v67, s0
	v_cndmask_b32_e64 v67, v67, 0, s[22:23]
	ds_write_b16 v181, v67 offset:816
	v_add_u32_e32 v67, 0x1de00, v66
	ds_read_b32 v67, v67
	v_mul_f32_e32 v68, v32, v68
	v_cvt_pk_bf16_f32 v68, v68, s0
	v_cndmask_b32_e64 v68, v68, 0, s[20:21]
	ds_write_b16 v181, v68 offset:544
	s_waitcnt lgkmcnt(1)
	v_sub_f32_e32 v68, v152, v67
	v_mul_f32_e32 v68, 0x3fb8aa3b, v68
	v_exp_f32_e32 v68, v68
	s_nop 0
	v_mul_f32_e32 v68, v2, v68
	v_cvt_pk_bf16_f32 v68, v68, s0
	v_cndmask_b32_e64 v68, v68, 0, s[82:83]
	ds_write_b16 v181, v68 offset:32
	v_sub_f32_e32 v68, v153, v67
	v_mul_f32_e32 v68, 0x3fb8aa3b, v68
	v_exp_f32_e32 v68, v68
	s_nop 0
	v_mul_f32_e32 v68, v3, v68
	v_cvt_pk_bf16_f32 v68, v68, s0
	v_cndmask_b32_e64 v68, v68, 0, s[86:87]
	ds_write_b16 v181, v68 offset:304
	v_sub_f32_e32 v68, v121, v67
	v_sub_f32_e32 v67, v119, v67
	v_mul_f32_e32 v68, 0x3fb8aa3b, v68
	v_mul_f32_e32 v67, 0x3fb8aa3b, v67
	v_exp_f32_e32 v68, v68
	v_exp_f32_e32 v67, v67
	v_mul_f32_e32 v68, v4, v68
	v_mul_f32_e32 v67, v5, v67
	v_cvt_pk_bf16_f32 v68, v68, s0
	v_cvt_pk_bf16_f32 v67, v67, s0
	v_cndmask_b32_e64 v68, v68, 0, s[88:89]
	v_cndmask_b32_e64 v67, v67, 0, s[90:91]
	ds_write_b16 v181, v68 offset:576
	ds_write_b16 v181, v67 offset:848
	s_cbranch_vccnz .LBB0_1350
	v_add_u32_e32 v67, 0x1e000, v66
	ds_read_b32 v67, v67
	v_readlane_b32 s36, v254, 25
	v_readlane_b32 s37, v254, 26
	s_waitcnt lgkmcnt(0)
	v_sub_f32_e32 v68, v152, v67
	v_mul_f32_e32 v68, 0x3fb8aa3b, v68
	v_exp_f32_e32 v68, v68
	s_nop 0
	v_mul_f32_e32 v68, v6, v68
	v_cvt_pk_bf16_f32 v68, v68, s0
	v_cndmask_b32_e64 v68, v68, 0, s[36:37]
	ds_write_b16 v181, v68 offset:64
	v_sub_f32_e32 v68, v153, v67
	v_mul_f32_e32 v68, 0x3fb8aa3b, v68
	v_exp_f32_e32 v68, v68
	v_readlane_b32 s36, v254, 7
	v_readlane_b32 s37, v254, 8
	v_mul_f32_e32 v68, v7, v68
	v_cvt_pk_bf16_f32 v68, v68, s0
	v_cndmask_b32_e64 v68, v68, 0, s[36:37]
	ds_write_b16 v181, v68 offset:336
	v_sub_f32_e32 v68, v121, v67
	v_mul_f32_e32 v68, 0x3fb8aa3b, v68
	v_exp_f32_e32 v68, v68
	v_sub_f32_e32 v67, v119, v67
	v_mul_f32_e32 v67, 0x3fb8aa3b, v67
	v_exp_f32_e32 v67, v67
	v_mul_f32_e32 v68, v8, v68
	v_readlane_b32 s36, v255, 19
	v_cvt_pk_bf16_f32 v68, v68, s0
	v_readlane_b32 s37, v255, 20
	v_mul_f32_e32 v67, v9, v67
	v_cvt_pk_bf16_f32 v67, v67, s0
	v_cndmask_b32_e64 v68, v68, 0, s[36:37]
	v_readlane_b32 s36, v255, 21
	v_readlane_b32 s37, v255, 22
	ds_write_b16 v181, v68 offset:608
	s_nop 0
	v_cndmask_b32_e64 v67, v67, 0, s[36:37]
	ds_write_b16 v181, v67 offset:880
	s_andn2_b64 vcc, exec, s[94:95]
	s_cbranch_vccz .LBB0_1351

.LBB0_1358:
	s_nop 0
	v_div_scale_f32 v86, s[70:71], v85, v85, 1.0
	v_rcp_f32_e32 v87, v86
	v_add_u32_e32 v148, s73, v125
	ds_read_b128 v[184:187], v148 offset:65280
	v_mul_f32_e32 v152, 0x3fb8aa3b, v152
	v_fma_f32 v88, -v86, v87, 1.0
	v_fmac_f32_e32 v87, v88, v87
	v_div_scale_f32 v88, vcc, 1.0, v85, 1.0
	v_mul_f32_e32 v89, v88, v87
	v_fma_f32 v90, -v86, v89, v88
	v_fmac_f32_e32 v89, v90, v87
	v_fma_f32 v86, -v86, v89, v88
	v_div_fmas_f32 v86, v86, v87, v89
	v_div_fixup_f32 v151, v86, v85, 1.0
	v_div_scale_f32 v85, s[70:71], v84, v84, 1.0
	v_rcp_f32_e32 v86, v85
	ds_read_b128 v[90:93], v148 offset:56576
	ds_read_b128 v[94:97], v148 offset:60928
	v_mul_f32_e32 v153, 0x3fb8aa3b, v153
	v_fma_f32 v87, -v85, v86, 1.0
	v_fmac_f32_e32 v86, v87, v86
	v_div_scale_f32 v87, vcc, 1.0, v84, 1.0
	v_mul_f32_e32 v88, v87, v86
	v_fma_f32 v89, -v85, v88, v87
	v_fmac_f32_e32 v88, v89, v86
	v_fma_f32 v85, -v85, v88, v87
	v_div_fmas_f32 v85, v85, v86, v88
	v_div_fixup_f32 v150, v85, v84, 1.0
	s_nop 0
	v_div_scale_f32 v84, s[70:71], v83, v83, 1.0
	v_rcp_f32_e32 v85, v84
	v_exp_f32_e32 v152, v152
	v_exp_f32_e32 v153, v153
	v_readlane_b32 s36, v254, 63
	v_fma_f32 v86, -v84, v85, 1.0
	v_fmac_f32_e32 v85, v86, v85
	v_div_scale_f32 v86, vcc, 1.0, v83, 1.0
	v_mul_f32_e32 v87, v86, v85
	v_fma_f32 v88, -v84, v87, v86
	v_fmac_f32_e32 v87, v88, v85
	v_fma_f32 v84, -v84, v87, v86
	v_div_fmas_f32 v84, v84, v85, v87
	v_div_fixup_f32 v147, v84, v83, 1.0
	v_div_scale_f32 v83, s[70:71], v82, v82, 1.0
	v_rcp_f32_e32 v84, v83
	v_readlane_b32 s50, v255, 13
	v_readlane_b32 s51, v255, 14
	v_readlane_b32 s37, v255, 0
	v_fma_f32 v85, -v83, v84, 1.0
	v_fmac_f32_e32 v84, v85, v84
	v_div_scale_f32 v85, vcc, 1.0, v82, 1.0
	v_mul_f32_e32 v86, v85, v84
	v_fma_f32 v87, -v83, v86, v85
	v_fmac_f32_e32 v86, v87, v84
	v_fma_f32 v83, -v83, v86, v85
	v_div_fmas_f32 v83, v83, v84, v86
	v_div_fixup_f32 v146, v83, v82, 1.0
	ds_read_b128 v[82:85], v113
	ds_read_b128 v[86:89], v148 offset:52224
	s_waitcnt lgkmcnt(0)
	v_mfma_f32_16x16x32_bf16 v[86:89], v[82:85], v[86:89], 0
	v_readlane_b32 s38, v255, 1
	v_readlane_b32 s39, v255, 2
	v_readlane_b32 s40, v255, 3
	v_mfma_f32_16x16x32_bf16 v[90:93], v[82:85], v[90:93], 0
	v_readlane_b32 s41, v255, 4
	v_readlane_b32 s42, v255, 5
	v_readlane_b32 s43, v255, 6
	v_mfma_f32_16x16x32_bf16 v[94:97], v[82:85], v[94:97], 0
	v_readlane_b32 s44, v255, 7
	v_readlane_b32 s45, v255, 8
	v_readlane_b32 s46, v255, 9
	v_mfma_f32_16x16x32_bf16 v[82:85], v[82:85], v[184:187], 0
	ds_read_b128 v[184:187], v113 offset:64
	ds_read_b128 v[188:191], v148 offset:52288
	v_readlane_b32 s47, v255, 10
	v_readlane_b32 s48, v255, 11
	s_waitcnt lgkmcnt(0)
	v_mfma_f32_16x16x32_bf16 v[86:89], v[184:187], v[188:191], v[86:89]
	ds_read_b128 v[188:191], v148 offset:56640
	v_readlane_b32 s49, v255, 12
	s_waitcnt lgkmcnt(0)
	v_mfma_f32_16x16x32_bf16 v[90:93], v[184:187], v[188:191], v[90:93]
	ds_read_b128 v[188:191], v148 offset:60992
	s_waitcnt lgkmcnt(0)
	v_mfma_f32_16x16x32_bf16 v[94:97], v[184:187], v[188:191], v[94:97]
	ds_read_b128 v[188:191], v148 offset:65344
	s_waitcnt lgkmcnt(0)
	v_mfma_f32_16x16x32_bf16 v[82:85], v[184:187], v[188:191], v[82:85]
	ds_read_b128 v[184:187], v113 offset:128
	ds_read_b128 v[188:191], v148 offset:52352
	s_waitcnt lgkmcnt(0)
	v_mfma_f32_16x16x32_bf16 v[86:89], v[184:187], v[188:191], v[86:89]
	ds_read_b128 v[188:191], v148 offset:56704
	s_waitcnt lgkmcnt(0)
	v_mfma_f32_16x16x32_bf16 v[90:93], v[184:187], v[188:191], v[90:93]
	ds_read_b128 v[188:191], v148 offset:61056
	s_waitcnt lgkmcnt(0)
	v_mfma_f32_16x16x32_bf16 v[188:191], v[184:187], v[188:191], v[94:97]
	s_nop 2
	ds_read_b128 v[94:97], v148 offset:65408
	s_waitcnt lgkmcnt(0)
	v_mfma_f32_16x16x32_bf16 v[82:85], v[184:187], v[94:97], v[82:85]
	ds_read_b128 v[184:187], v113 offset:192
	ds_read_b128 v[94:97], v148 offset:52416
	s_waitcnt lgkmcnt(0)
	v_mfma_f32_16x16x32_bf16 v[94:97], v[184:187], v[94:97], v[86:89]
	s_nop 2
	ds_read_b128 v[86:89], v148 offset:56768
	s_waitcnt lgkmcnt(0)
	v_mfma_f32_16x16x32_bf16 v[90:93], v[184:187], v[86:89], v[90:93]
	ds_read_b128 v[86:89], v148 offset:61120
	s_nop 0
	v_pk_fma_f32 v[78:79], v[152:153], v[94:95], v[78:79]
	s_nop 4
	v_pk_fma_f32 v[90:91], v[152:153], v[90:91], v[74:75]
	s_waitcnt lgkmcnt(0)
	v_mfma_f32_16x16x32_bf16 v[86:89], v[184:187], v[86:89], v[188:191]
	s_nop 2
	ds_read_b128 v[188:191], v148 offset:65472
	s_waitcnt lgkmcnt(0)
	v_mfma_f32_16x16x32_bf16 v[82:85], v[184:187], v[188:191], v[82:85]
	ds_read_u16 v183, v117 offset:17408
	ds_read_u16 v187, v117 offset:17440
	ds_read_u16 v184, v178
	ds_read_u16 v185, v178 offset:32
	ds_read_u16 v190, v117 offset:17472
	ds_read_u16 v191, v178 offset:64
	ds_read_u16 v192, v117 offset:17504
	ds_read_u16 v186, v178 offset:96
	ds_read_u16 v188, v117 offset:17680
	ds_read_u16 v189, v178 offset:128
	ds_read_u16 v193, v117 offset:17712
	ds_read_u16 v194, v178 offset:160
	ds_read_u16 v195, v117 offset:17744
	ds_read_u16 v196, v178 offset:192
	ds_read_u16 v197, v117 offset:17776
	ds_read_u16 v198, v178 offset:224
	s_waitcnt lgkmcnt(13)
	v_lshlrev_b32_e32 v200, 16, v184
	s_waitcnt lgkmcnt(12)
	v_lshlrev_b32_e32 v201, 16, v185
	v_mul_f32_e32 v184, 0xbfb8aa3b, v200
	v_mul_f32_e32 v185, 0xbfb8aa3b, v201
	s_waitcnt lgkmcnt(8)
	v_lshlrev_b32_e32 v199, 16, v186
	v_exp_f32_e32 v184, v184
	v_exp_f32_e32 v186, v185
	s_waitcnt lgkmcnt(4)
	v_lshlrev_b32_e32 v194, 16, v194
	v_mul_f32_e32 v74, 0xbfb8aa3b, v194
	v_pk_fma_f32 v[70:71], v[152:153], v[86:87], v[70:71]
	s_waitcnt lgkmcnt(0)
	v_lshlrev_b32_e32 v198, 16, v198
	v_pk_fma_f32 v[66:67], v[152:153], v[82:83], v[66:67]
	v_mul_f32_e32 v82, 0xbfb8aa3b, v198
	s_cmp_eq_u32 s33, 12
	s_cbranch_scc1 .Lssd_w2c
	s_cmp_lg_u64 s[14:15], 0
	s_cbranch_scc1 .Lssd_w2b
	s_waitcnt vmcnt(14)
	s_branch .Lssd_w2d
.Lssd_w2b:
	s_waitcnt vmcnt(18)
	s_branch .Lssd_w2d

.Lssd_w2d:
	v_mov_b32_e32 v148, v238
	v_pk_mul_f32 v[154:155], v[150:151], v[148:149] op_sel_hi:[1,0]
	v_lshlrev_b32_e32 v151, 16, v189
	v_mul_f32_e32 v94, 0xbfb8aa3b, v151
	v_exp_f32_e32 v185, v94
	v_lshlrev_b32_e32 v189, 16, v188
	v_lshlrev_b32_e32 v188, 16, v183
	v_mul_f32_e32 v150, 0xbfb8aa3b, v199
	v_pk_add_f32 v[94:95], v[184:185], 1.0 op_sel_hi:[1,0]
	v_exp_f32_e32 v150, v150
	v_div_scale_f32 v183, s[70:71], v95, v95, v151
	v_rcp_f32_e32 v184, v183
	s_nop 0
	v_fma_f32 v185, -v183, v184, 1.0
	v_fmac_f32_e32 v184, v185, v184
	v_div_scale_f32 v185, vcc, v151, v95, v151
	v_mul_f32_e32 v202, v185, v184
	v_fma_f32 v203, -v183, v202, v185
	v_fmac_f32_e32 v202, v203, v184
	v_fma_f32 v183, -v183, v202, v185
	v_div_fmas_f32 v183, v183, v184, v202
	v_div_fixup_f32 v95, v183, v95, v151
	v_div_scale_f32 v151, s[70:71], v94, v94, v200
	v_rcp_f32_e32 v183, v151
	s_nop 0
	v_fma_f32 v184, -v151, v183, 1.0
	v_fmac_f32_e32 v183, v184, v183
	v_div_scale_f32 v184, vcc, v200, v94, v200
	v_mul_f32_e32 v185, v184, v183
	v_fma_f32 v202, -v151, v185, v184
	v_fmac_f32_e32 v185, v202, v183
	v_fma_f32 v151, -v151, v185, v184
	v_lshlrev_b32_e32 v184, 16, v187
	v_exp_f32_e32 v187, v74
	v_div_fmas_f32 v151, v151, v183, v185
	v_div_fixup_f32 v94, v151, v94, v200
	v_lshlrev_b32_e32 v185, 16, v193
	v_pk_add_f32 v[74:75], v[186:187], 1.0 op_sel_hi:[1,0]
	s_nop 0
	v_div_scale_f32 v151, s[70:71], v75, v75, v194
	v_rcp_f32_e32 v183, v151
	s_nop 0
	v_fma_f32 v186, -v151, v183, 1.0
	v_fmac_f32_e32 v183, v186, v183
	v_div_scale_f32 v186, vcc, v194, v75, v194
	v_mul_f32_e32 v187, v186, v183
	v_fma_f32 v193, -v151, v187, v186
	v_fmac_f32_e32 v187, v193, v183
	v_fma_f32 v151, -v151, v187, v186
	v_div_fmas_f32 v151, v151, v183, v187
	v_div_fixup_f32 v187, v151, v75, v194
	v_div_scale_f32 v75, s[70:71], v74, v74, v201
	v_rcp_f32_e32 v151, v75
	s_nop 0
	v_fma_f32 v183, -v75, v151, 1.0
	v_fmac_f32_e32 v151, v183, v151
	v_div_scale_f32 v183, vcc, v201, v74, v201
	v_mul_f32_e32 v186, v183, v151
	v_fma_f32 v193, -v75, v186, v183
	v_fmac_f32_e32 v186, v193, v151
	v_fma_f32 v75, -v75, v186, v183
	v_div_fmas_f32 v75, v75, v151, v186
	v_lshlrev_b32_e32 v151, 16, v196
	v_lshlrev_b32_e32 v183, 16, v191
	v_div_fixup_f32 v186, v75, v74, v201
	v_pk_fma_f32 v[74:75], v[154:155], v[188:189], v[78:79]
	v_pk_fma_f32 v[78:79], v[154:155], v[184:185], v[90:91]
	v_mul_f32_e32 v90, 0xbfb8aa3b, v183
	v_mul_f32_e32 v86, 0xbfb8aa3b, v151
	v_exp_f32_e32 v90, v90
	v_exp_f32_e32 v91, v86
	v_pk_mul_f32 v[78:79], v[78:79], v[186:187]
	v_pk_mul_f32 v[74:75], v[74:75], v[94:95]
	v_lshlrev_b32_e32 v95, 16, v195
	v_pk_add_f32 v[86:87], v[90:91], 1.0 op_sel_hi:[1,0]
	v_lshlrev_b32_e32 v94, 16, v190
	v_div_scale_f32 v90, s[70:71], v87, v87, v151
	v_rcp_f32_e32 v91, v90
	v_pk_fma_f32 v[70:71], v[154:155], v[94:95], v[70:71]
	v_fma_f32 v184, -v90, v91, 1.0
	v_fmac_f32_e32 v91, v184, v91
	v_div_scale_f32 v184, vcc, v151, v87, v151
	v_mul_f32_e32 v185, v184, v91
	v_fma_f32 v186, -v90, v185, v184
	v_fmac_f32_e32 v185, v186, v91
	v_fma_f32 v90, -v90, v185, v184
	v_div_fmas_f32 v90, v90, v91, v185
	v_div_fixup_f32 v87, v90, v87, v151
	v_div_scale_f32 v90, s[70:71], v86, v86, v183
	v_rcp_f32_e32 v91, v90
	s_nop 0
	v_fma_f32 v151, -v90, v91, 1.0
	v_fmac_f32_e32 v91, v151, v91
	v_div_scale_f32 v151, vcc, v183, v86, v183
	v_mul_f32_e32 v184, v151, v91
	v_fma_f32 v185, -v90, v184, v151
	v_fmac_f32_e32 v184, v185, v91
	v_fma_f32 v90, -v90, v184, v151
	v_exp_f32_e32 v151, v82
	v_div_fmas_f32 v90, v90, v91, v184
	v_div_fixup_f32 v86, v90, v86, v183
	v_pk_mul_f32 v[70:71], v[70:71], v[86:87]
	v_lshlrev_b32_e32 v87, 16, v197
	v_lshlrev_b32_e32 v86, 16, v192
	v_pk_add_f32 v[82:83], v[150:151], 1.0 op_sel_hi:[1,0]
	v_pk_fma_f32 v[66:67], v[154:155], v[86:87], v[66:67]
	v_div_scale_f32 v86, s[70:71], v83, v83, v198
	v_rcp_f32_e32 v87, v86
	s_nop 0
	v_fma_f32 v90, -v86, v87, 1.0
	v_fmac_f32_e32 v87, v90, v87
	v_div_scale_f32 v90, vcc, v198, v83, v198
	v_mul_f32_e32 v91, v90, v87
	v_fma_f32 v94, -v86, v91, v90
	v_fmac_f32_e32 v91, v94, v87
	v_fma_f32 v86, -v86, v91, v90
	v_div_fmas_f32 v86, v86, v87, v91
	v_div_fixup_f32 v83, v86, v83, v198
	v_div_scale_f32 v86, s[70:71], v82, v82, v199
	v_rcp_f32_e32 v87, v86
	s_nop 0
	v_fma_f32 v90, -v86, v87, 1.0
	v_fmac_f32_e32 v87, v90, v87
	v_div_scale_f32 v90, vcc, v199, v82, v199
	v_mul_f32_e32 v91, v90, v87
	v_fma_f32 v94, -v86, v91, v90
	v_fmac_f32_e32 v91, v94, v87
	v_fma_f32 v86, -v86, v91, v90
	v_div_fmas_f32 v86, v86, v87, v91
	v_div_fixup_f32 v82, v86, v82, v199
	v_pk_mul_f32 v[66:67], v[66:67], v[82:83]
	v_mul_f32_e32 v82, 0x3fb8aa3b, v121
	ds_read_u16 v87, v117 offset:17952
	ds_read_u16 v94, v178 offset:256
	ds_read_u16 v121, v117 offset:17984
	ds_read_u16 v95, v178 offset:288
	ds_read_u16 v152, v117 offset:18016
	ds_read_u16 v153, v178 offset:320
	ds_read_u16 v154, v117 offset:18048
	ds_read_u16 v86, v178 offset:352
	v_mul_f32_e32 v83, 0x3fb8aa3b, v119
	ds_read_u16 v119, v117 offset:18224
	ds_read_u16 v150, v178 offset:384
	ds_read_u16 v155, v117 offset:18256
	ds_read_u16 v151, v178 offset:416
	ds_read_u16 v183, v117 offset:18288
	ds_read_u16 v184, v178 offset:448
	ds_read_u16 v185, v117 offset:18320
	ds_read_u16 v186, v178 offset:480
	v_pk_mul_f32 v[90:91], v[146:147], v[148:149] op_sel_hi:[1,0]
	s_waitcnt lgkmcnt(6)
	v_lshlrev_b32_e32 v147, 16, v150
	v_lshlrev_b32_e32 v187, 16, v94
	v_lshlrev_b32_e32 v189, 16, v95
	v_mul_f32_e32 v94, 0xbfb8aa3b, v187
	v_mul_f32_e32 v95, 0xbfb8aa3b, v189
	v_lshlrev_b32_e32 v150, 16, v87
	v_mul_f32_e32 v87, 0xbfb8aa3b, v147
	v_exp_f32_e32 v94, v94
	v_exp_f32_e32 v146, v95
	v_exp_f32_e32 v95, v87
	v_exp_f32_e32 v82, v82
	v_exp_f32_e32 v83, v83
	s_waitcnt lgkmcnt(4)
	v_lshlrev_b32_e32 v188, 16, v151
	v_pk_add_f32 v[94:95], v[94:95], 1.0 op_sel_hi:[1,0]
	v_lshlrev_b32_e32 v151, 16, v119
	v_div_scale_f32 v87, s[70:71], v95, v95, v147
	v_pk_fma_f32 v[80:81], v[82:83], v[96:97], v[80:81]
	v_rcp_f32_e32 v96, v87
	v_pk_fma_f32 v[92:93], v[82:83], v[92:93], v[76:77]
	v_mul_f32_e32 v76, 0xbfb8aa3b, v188
	v_pk_fma_f32 v[72:73], v[82:83], v[88:89], v[72:73]
	v_fma_f32 v97, -v87, v96, 1.0
	v_fmac_f32_e32 v96, v97, v96
	v_div_scale_f32 v97, vcc, v147, v95, v147
	v_mul_f32_e32 v119, v97, v96
	v_fma_f32 v190, -v87, v119, v97
	v_fmac_f32_e32 v119, v190, v96
	v_fma_f32 v87, -v87, v119, v97
	v_div_fmas_f32 v87, v87, v96, v119
	v_div_fixup_f32 v95, v87, v95, v147
	v_div_scale_f32 v87, s[70:71], v94, v94, v187
	v_rcp_f32_e32 v96, v87
	s_waitcnt lgkmcnt(0)
	v_lshlrev_b32_e32 v148, 16, v186
	v_lshlrev_b32_e32 v186, 16, v86
	v_mul_f32_e32 v86, 0xbfb8aa3b, v186
	v_fma_f32 v97, -v87, v96, 1.0
	v_fmac_f32_e32 v96, v97, v96
	v_div_scale_f32 v97, vcc, v187, v94, v187
	v_mul_f32_e32 v119, v97, v96
	v_fma_f32 v147, -v87, v119, v97
	v_fmac_f32_e32 v119, v147, v96
	v_exp_f32_e32 v147, v76
	v_fma_f32 v87, -v87, v119, v97
	v_div_fmas_f32 v87, v87, v96, v119
	v_div_fixup_f32 v94, v87, v94, v187
	v_pk_add_f32 v[76:77], v[146:147], 1.0 op_sel_hi:[1,0]
	v_lshlrev_b32_e32 v96, 16, v121
	v_div_scale_f32 v87, s[70:71], v77, v77, v188
	v_rcp_f32_e32 v119, v87
	v_lshlrev_b32_e32 v97, 16, v155
	v_pk_fma_f32 v[68:69], v[82:83], v[84:85], v[68:69]
	v_mul_f32_e32 v82, 0xbfb8aa3b, v148
	v_fma_f32 v121, -v87, v119, 1.0
	v_fmac_f32_e32 v119, v121, v119
	v_div_scale_f32 v121, vcc, v188, v77, v188
	v_mul_f32_e32 v146, v121, v119
	v_fma_f32 v147, -v87, v146, v121
	v_fmac_f32_e32 v146, v147, v119
	v_fma_f32 v87, -v87, v146, v121
	v_div_fmas_f32 v87, v87, v119, v146
	v_div_fixup_f32 v147, v87, v77, v188
	v_div_scale_f32 v77, s[70:71], v76, v76, v189
	v_rcp_f32_e32 v87, v77
	v_exp_f32_e32 v86, v86
	s_waitcnt lgkmcnt(0)
	v_fma_f32 v119, -v77, v87, 1.0
	v_fmac_f32_e32 v87, v119, v87
	v_div_scale_f32 v119, vcc, v189, v76, v189
	v_mul_f32_e32 v121, v119, v87
	v_fma_f32 v146, -v77, v121, v119
	v_fmac_f32_e32 v121, v146, v87
	v_fma_f32 v77, -v77, v121, v119
	v_div_fmas_f32 v77, v77, v87, v121
	v_div_fixup_f32 v146, v77, v76, v189
	v_pk_fma_f32 v[76:77], v[90:91], v[150:151], v[80:81]
	v_pk_fma_f32 v[80:81], v[90:91], v[96:97], v[92:93]
	v_lshlrev_b32_e32 v87, 16, v184
	v_lshlrev_b32_e32 v96, 16, v153
	v_mul_f32_e32 v92, 0xbfb8aa3b, v96
	v_mul_f32_e32 v88, 0xbfb8aa3b, v87
	v_exp_f32_e32 v92, v92
	v_exp_f32_e32 v93, v88
	v_pk_mul_f32 v[76:77], v[76:77], v[94:95]
	v_lshlrev_b32_e32 v95, 16, v183
	v_lshlrev_b32_e32 v94, 16, v152
	v_pk_add_f32 v[88:89], v[92:93], 1.0 op_sel_hi:[1,0]
	v_pk_fma_f32 v[72:73], v[90:91], v[94:95], v[72:73]
	v_div_scale_f32 v92, s[70:71], v89, v89, v87
	v_rcp_f32_e32 v93, v92
	v_pk_mul_f32 v[80:81], v[80:81], v[146:147]
	v_fma_f32 v97, -v92, v93, 1.0
	v_fmac_f32_e32 v93, v97, v93
	v_div_scale_f32 v97, vcc, v87, v89, v87
	v_mul_f32_e32 v119, v97, v93
	v_fma_f32 v121, -v92, v119, v97
	v_fmac_f32_e32 v119, v121, v93
	v_fma_f32 v92, -v92, v119, v97
	v_div_fmas_f32 v92, v92, v93, v119
	v_div_fixup_f32 v89, v92, v89, v87
	v_div_scale_f32 v87, s[70:71], v88, v88, v96
	v_rcp_f32_e32 v92, v87
	s_nop 0
	v_fma_f32 v93, -v87, v92, 1.0
	v_fmac_f32_e32 v92, v93, v92
	v_div_scale_f32 v93, vcc, v96, v88, v96
	v_mul_f32_e32 v97, v93, v92
	v_fma_f32 v119, -v87, v97, v93
	v_fmac_f32_e32 v97, v119, v92
	v_fma_f32 v87, -v87, v97, v93
	v_div_fmas_f32 v87, v87, v92, v97
	v_div_fixup_f32 v88, v87, v88, v96
	v_exp_f32_e32 v87, v82
	v_pk_mul_f32 v[72:73], v[72:73], v[88:89]
	v_lshlrev_b32_e32 v89, 16, v185
	v_lshlrev_b32_e32 v88, 16, v154
	v_pk_add_f32 v[82:83], v[86:87], 1.0 op_sel_hi:[1,0]
	v_pk_fma_f32 v[68:69], v[90:91], v[88:89], v[68:69]
	v_div_scale_f32 v84, s[70:71], v83, v83, v148
	v_rcp_f32_e32 v85, v84
	v_lshl_add_u64 v[90:91], s[50:51], 0, v[142:143]
	v_fma_f32 v86, -v84, v85, 1.0
	v_fmac_f32_e32 v85, v86, v85
	v_div_scale_f32 v86, vcc, v148, v83, v148
	v_mul_f32_e32 v87, v86, v85
	v_fma_f32 v88, -v84, v87, v86
	v_fmac_f32_e32 v87, v88, v85
	v_fma_f32 v84, -v84, v87, v86
	v_div_fmas_f32 v84, v84, v85, v87
	v_div_fixup_f32 v83, v84, v83, v148
	v_div_scale_f32 v84, s[70:71], v82, v82, v186
	v_rcp_f32_e32 v85, v84
	s_nop 0
	v_fma_f32 v86, -v84, v85, 1.0
	v_fmac_f32_e32 v85, v86, v85
	v_div_scale_f32 v86, vcc, v186, v82, v186
	v_mul_f32_e32 v87, v86, v85
	v_fma_f32 v88, -v84, v87, v86
	v_fmac_f32_e32 v87, v88, v85
	v_fma_f32 v84, -v84, v87, v86
	v_div_fmas_f32 v84, v84, v85, v87
	v_div_fixup_f32 v82, v84, v82, v186
	v_pk_mul_f32 v[68:69], v[68:69], v[82:83]
	v_cvt_pk_bf16_f32 v82, v74, s0
	ds_write_b16 v178, v82
	v_cvt_pk_bf16_f32 v82, v78, s0
	ds_write_b16 v178, v82 offset:32
	v_cvt_pk_bf16_f32 v82, v70, s0
	ds_write_b16 v178, v82 offset:64
	v_cvt_pk_bf16_f32 v82, v66, s0
	ds_write_b16 v178, v82 offset:96
	v_cvt_pk_bf16_f32 v82, v75, s0
	ds_write_b16 v178, v82 offset:128
	v_cvt_pk_bf16_f32 v82, v79, s0
	ds_write_b16 v178, v82 offset:160
	v_cvt_pk_bf16_f32 v82, v71, s0
	ds_write_b16 v178, v82 offset:192
	v_cvt_pk_bf16_f32 v82, v67, s0
	ds_write_b16 v178, v82 offset:224
	v_cvt_pk_bf16_f32 v82, v76, s0
	ds_write_b16 v178, v82 offset:256
	v_cvt_pk_bf16_f32 v82, v80, s0
	ds_write_b16 v178, v82 offset:288
	v_cvt_pk_bf16_f32 v82, v72, s0
	ds_write_b16 v178, v82 offset:320
	v_cvt_pk_bf16_f32 v82, v68, s0
	ds_write_b16 v178, v82 offset:352
	v_cvt_pk_bf16_f32 v82, v77, s0
	ds_write_b16 v178, v82 offset:384
	v_cvt_pk_bf16_f32 v82, v81, s0
	ds_write_b16 v178, v82 offset:416
	v_cvt_pk_bf16_f32 v82, v73, s0
	ds_write_b16 v178, v82 offset:448
	v_cvt_pk_bf16_f32 v82, v69, s0
	ds_write_b16 v178, v82 offset:480
	s_waitcnt lgkmcnt(0)
	ds_read_b128 v[82:85], v180
	ds_read_b128 v[86:89], v180 offset:1024
	v_add_co_u32_e32 v92, vcc, 0x10000000, v90
	s_nop 1
	v_addc_co_u32_e32 v93, vcc, 0, v91, vcc
	s_waitcnt lgkmcnt(1)
	global_store_dwordx4 v[92:93], v[82:85], off offset:2048
	s_nop 1
	v_add_co_u32_e32 v82, vcc, 0x10008000, v90
	s_nop 1
	v_addc_co_u32_e32 v83, vcc, 0, v91, vcc
	s_andn2_b64 vcc, exec, s[66:67]
	s_waitcnt lgkmcnt(0)
	global_store_dwordx4 v[82:83], v[86:89], off offset:2048
	s_barrier
	s_waitcnt vmcnt(2)
	ds_write_b128 v180, v[226:229]
	ds_write_b128 v180, v[230:233] offset:1024
	s_cbranch_vccnz .LBB0_1336
	v_lshlrev_b32_e32 v82, 16, v38
	v_and_b32_e32 v83, 0xffff0000, v38
	v_lshlrev_b32_e32 v84, 16, v39
	v_and_b32_e32 v85, 0xffff0000, v39
	v_pk_mul_f32 v[82:83], v[122:123], v[82:83] op_sel_hi:[0,1]
	v_pk_mul_f32 v[84:85], v[122:123], v[84:85] op_sel_hi:[0,1]
	v_cvt_pk_bf16_f32 v82, v82, v83
	v_cvt_pk_bf16_f32 v83, v84, v85
	v_lshlrev_b32_e32 v84, 16, v40
	v_and_b32_e32 v85, 0xffff0000, v40
	v_lshlrev_b32_e32 v86, 16, v41
	v_and_b32_e32 v87, 0xffff0000, v41
	v_pk_mul_f32 v[84:85], v[122:123], v[84:85] op_sel_hi:[0,1]
	v_pk_mul_f32 v[86:87], v[122:123], v[86:87] op_sel_hi:[0,1]
	v_cvt_pk_bf16_f32 v84, v84, v85
	v_cvt_pk_bf16_f32 v85, v86, v87
	ds_write_b128 v127, v[82:85] offset:17408
	ds_write_b128 v127, v[42:45] offset:52224
	s_and_saveexec_b64 s[66:67], s[10:11]
	s_cbranch_execz .LBB0_1364
	v_lshlrev_b32_e32 v82, 16, v34
	v_and_b32_e32 v83, 0xffff0000, v34
	v_lshlrev_b32_e32 v84, 16, v35
	v_and_b32_e32 v85, 0xffff0000, v35
	v_pk_mul_f32 v[82:83], v[124:125], v[82:83] op_sel_hi:[0,1]
	v_pk_mul_f32 v[84:85], v[124:125], v[84:85] op_sel_hi:[0,1]
	v_cvt_pk_bf16_f32 v82, v82, v83
	v_cvt_pk_bf16_f32 v83, v84, v85
	v_lshlrev_b32_e32 v84, 16, v36
	v_and_b32_e32 v85, 0xffff0000, v36
	v_lshlrev_b32_e32 v86, 16, v37
	v_and_b32_e32 v87, 0xffff0000, v37
	v_pk_mul_f32 v[84:85], v[124:125], v[84:85] op_sel_hi:[0,1]
	v_pk_mul_f32 v[86:87], v[124:125], v[86:87] op_sel_hi:[0,1]
	v_cvt_pk_bf16_f32 v84, v84, v85
	v_cvt_pk_bf16_f32 v85, v86, v87
	ds_write_b128 v127, v[82:85] offset:26112
	s_or_b64 exec, exec, s[66:67]
	ds_write_b128 v127, v[54:57] offset:60928
	s_and_saveexec_b64 s[66:67], s[12:13]
	s_cbranch_execnz .LBB0_1365
